# v_g2 + trailing half takes its restore-offset barrier after the 6th epilogue store (next tile's first MFMA block overlaps the epilogue tail) in P1/P6
# baseline (speedup 1.0000x reference)
.Lepibar_p1:
	v_cvt_pk_bf16_f32 v88, v88, v89
	v_cvt_pk_bf16_f32 v89, v90, v91
	v_pk_fma_f32 v[90:91], v[98:99], v[92:93], v[98:99] op_sel_hi:[0,1,0]
	v_rcp_f32_e32 v90, v90
	v_rcp_f32_e32 v91, v91
	v_pk_fma_f32 v[92:93], v[98:99], v[94:95], v[98:99] op_sel_hi:[0,1,0]
	v_rcp_f32_e32 v92, v92
	v_rcp_f32_e32 v93, v93
	v_pk_mul_f32 v[80:81], v[80:81], v[84:85]
	v_pk_mul_f32 v[82:83], v[82:83], v[86:87]
	v_pk_mul_f32 v[80:81], v[80:81], v[90:91]
	v_pk_mul_f32 v[82:83], v[82:83], v[92:93]
	v_cvt_pk_bf16_f32 v90, v80, v81
	v_mul_f32_e32 v80, 0xbfb8aa3b, v139
	v_mul_f32_e32 v81, v139, v139
	v_pk_mul_f32 v[84:85], v[72:73], v[80:81] op_sel_hi:[1,0]
	v_pk_mul_f32 v[86:87], v[74:75], v[80:81] op_sel_hi:[1,0]
	v_cvt_pk_bf16_f32 v91, v82, v83
	v_rcp_f32_e32 v82, v81
	v_exp_f32_e32 v84, v84
	v_exp_f32_e32 v85, v85
	v_exp_f32_e32 v86, v86
	v_exp_f32_e32 v87, v87
	v_pk_mul_f32 v[72:73], v[72:73], v[76:77]
	v_pk_fma_f32 v[84:85], v[82:83], v[84:85], v[82:83] op_sel_hi:[0,1,0]
	v_rcp_f32_e32 v84, v84
	v_pk_fma_f32 v[86:87], v[82:83], v[86:87], v[82:83] op_sel_hi:[0,1,0]
	v_rcp_f32_e32 v85, v85
	v_rcp_f32_e32 v86, v86
	v_rcp_f32_e32 v87, v87
	v_pk_mul_f32 v[76:77], v[56:57], v[80:81] op_sel_hi:[1,0]
	v_pk_mul_f32 v[74:75], v[74:75], v[78:79]
	v_exp_f32_e32 v76, v76
	v_exp_f32_e32 v77, v77
	v_pk_mul_f32 v[78:79], v[58:59], v[80:81] op_sel_hi:[1,0]
	v_add_co_u32_e32 v92, vcc, s75, v132
	v_exp_f32_e32 v78, v78
	v_exp_f32_e32 v79, v79
	v_addc_co_u32_e32 v93, vcc, 0, v133, vcc
	v_pk_mul_f32 v[72:73], v[72:73], v[84:85]
	v_pk_mul_f32 v[74:75], v[74:75], v[86:87]
	global_store_dwordx4 v[92:93], v[88:91], off
	v_cvt_pk_bf16_f32 v72, v72, v73
	v_cvt_pk_bf16_f32 v73, v74, v75
	v_pk_fma_f32 v[74:75], v[82:83], v[76:77], v[82:83] op_sel_hi:[0,1,0]
	v_rcp_f32_e32 v74, v74
	v_rcp_f32_e32 v75, v75
	v_pk_fma_f32 v[76:77], v[82:83], v[78:79], v[82:83] op_sel_hi:[0,1,0]
	v_rcp_f32_e32 v76, v76
	v_rcp_f32_e32 v77, v77
	v_pk_mul_f32 v[56:57], v[56:57], v[64:65]
	v_pk_mul_f32 v[58:59], v[58:59], v[66:67]
	v_pk_mul_f32 v[56:57], v[56:57], v[74:75]
	v_pk_mul_f32 v[58:59], v[58:59], v[76:77]
	v_cvt_pk_bf16_f32 v74, v56, v57
	s_waitcnt lgkmcnt(1)
	v_mul_f32_e32 v56, 0xbfb8aa3b, v136
	v_mul_f32_e32 v57, v136, v136
	v_pk_mul_f32 v[64:65], v[60:61], v[56:57] op_sel_hi:[1,0]
	v_cvt_pk_bf16_f32 v75, v58, v59
	v_rcp_f32_e32 v58, v57
	v_exp_f32_e32 v64, v64
	v_exp_f32_e32 v65, v65
	v_pk_mul_f32 v[66:67], v[62:63], v[56:57] op_sel_hi:[1,0]
	v_pk_mul_f32 v[60:61], v[60:61], v[68:69]
	v_exp_f32_e32 v66, v66
	v_exp_f32_e32 v67, v67
	v_pk_fma_f32 v[64:65], v[58:59], v[64:65], v[58:59] op_sel_hi:[0,1,0]
	v_rcp_f32_e32 v64, v64
	v_rcp_f32_e32 v65, v65
	v_pk_fma_f32 v[66:67], v[58:59], v[66:67], v[58:59] op_sel_hi:[0,1,0]
	v_rcp_f32_e32 v66, v66
	v_rcp_f32_e32 v67, v67
	v_pk_mul_f32 v[60:61], v[60:61], v[64:65]
	v_pk_mul_f32 v[64:65], v[48:49], v[56:57] op_sel_hi:[1,0]
	v_pk_mul_f32 v[62:63], v[62:63], v[70:71]
	v_pk_mul_f32 v[56:57], v[50:51], v[56:57] op_sel_hi:[1,0]
	v_exp_f32_e32 v64, v64
	v_exp_f32_e32 v65, v65
	v_pk_mul_f32 v[62:63], v[62:63], v[66:67]
	v_exp_f32_e32 v66, v56
	v_exp_f32_e32 v67, v57
	v_add_co_u32_e32 v76, vcc, s76, v132
	v_pk_mul_f32 v[48:49], v[48:49], v[52:53]
	s_nop 0
	v_addc_co_u32_e32 v77, vcc, 0, v133, vcc
	global_store_dwordx4 v[76:77], v[72:75], off
	v_cvt_pk_bf16_f32 v56, v60, v61
	v_pk_fma_f32 v[60:61], v[58:59], v[64:65], v[58:59] op_sel_hi:[0,1,0]
	v_pk_fma_f32 v[58:59], v[58:59], v[66:67], v[58:59] op_sel_hi:[0,1,0]
	v_rcp_f32_e32 v60, v60
	v_rcp_f32_e32 v61, v61
	v_rcp_f32_e32 v58, v58
	v_rcp_f32_e32 v59, v59
	v_pk_mul_f32 v[50:51], v[50:51], v[54:55]
	v_pk_mul_f32 v[48:49], v[48:49], v[60:61]
	v_cvt_pk_bf16_f32 v57, v62, v63
	v_pk_mul_f32 v[50:51], v[50:51], v[58:59]
	v_cvt_pk_bf16_f32 v58, v48, v49
	v_mul_f32_e32 v48, 0xbfb8aa3b, v137
	v_mul_f32_e32 v49, v137, v137
	v_pk_mul_f32 v[52:53], v[40:41], v[48:49] op_sel_hi:[1,0]
	v_pk_mul_f32 v[54:55], v[42:43], v[48:49] op_sel_hi:[1,0]
	v_cvt_pk_bf16_f32 v59, v50, v51
	v_rcp_f32_e32 v50, v49
	v_exp_f32_e32 v52, v52
	v_exp_f32_e32 v53, v53
	v_exp_f32_e32 v54, v54
	v_exp_f32_e32 v55, v55
	v_pk_mul_f32 v[40:41], v[40:41], v[44:45]
	v_pk_fma_f32 v[52:53], v[50:51], v[52:53], v[50:51] op_sel_hi:[0,1,0]
	v_rcp_f32_e32 v52, v52
	v_pk_fma_f32 v[54:55], v[50:51], v[54:55], v[50:51] op_sel_hi:[0,1,0]
	v_rcp_f32_e32 v53, v53
	v_rcp_f32_e32 v54, v54
	v_rcp_f32_e32 v55, v55
	v_pk_mul_f32 v[44:45], v[32:33], v[48:49] op_sel_hi:[1,0]
	v_pk_mul_f32 v[42:43], v[42:43], v[46:47]
	v_exp_f32_e32 v44, v44
	v_exp_f32_e32 v45, v45
	v_pk_mul_f32 v[46:47], v[34:35], v[48:49] op_sel_hi:[1,0]
	v_add_co_u32_e32 v60, vcc, s77, v132
	v_exp_f32_e32 v46, v46
	v_exp_f32_e32 v47, v47
	v_addc_co_u32_e32 v61, vcc, 0, v133, vcc
	v_pk_mul_f32 v[40:41], v[40:41], v[52:53]
	v_pk_mul_f32 v[42:43], v[42:43], v[54:55]
	global_store_dwordx4 v[60:61], v[56:59], off
	v_cvt_pk_bf16_f32 v40, v40, v41
	v_cvt_pk_bf16_f32 v41, v42, v43
	v_pk_fma_f32 v[42:43], v[50:51], v[44:45], v[50:51] op_sel_hi:[0,1,0]
	v_rcp_f32_e32 v42, v42
	v_rcp_f32_e32 v43, v43
	v_pk_fma_f32 v[44:45], v[50:51], v[46:47], v[50:51] op_sel_hi:[0,1,0]
	v_rcp_f32_e32 v44, v44
	v_rcp_f32_e32 v45, v45
	v_pk_mul_f32 v[32:33], v[32:33], v[36:37]
	v_pk_mul_f32 v[34:35], v[34:35], v[38:39]
	v_pk_mul_f32 v[32:33], v[32:33], v[42:43]
	v_pk_mul_f32 v[34:35], v[34:35], v[44:45]
	v_cvt_pk_bf16_f32 v42, v32, v33
	s_waitcnt lgkmcnt(0)
	v_mul_f32_e32 v32, 0xbfb8aa3b, v134
	v_mul_f32_e32 v33, v134, v134
	v_pk_mul_f32 v[36:37], v[24:25], v[32:33] op_sel_hi:[1,0]
	v_pk_mul_f32 v[38:39], v[26:27], v[32:33] op_sel_hi:[1,0]
	v_cvt_pk_bf16_f32 v43, v34, v35
	v_rcp_f32_e32 v34, v33
	v_exp_f32_e32 v36, v36
	v_exp_f32_e32 v37, v37
	v_exp_f32_e32 v38, v38
	v_exp_f32_e32 v39, v39
	v_pk_mul_f32 v[24:25], v[24:25], v[28:29]
	v_pk_fma_f32 v[36:37], v[34:35], v[36:37], v[34:35] op_sel_hi:[0,1,0]
	v_rcp_f32_e32 v36, v36
	v_pk_fma_f32 v[38:39], v[34:35], v[38:39], v[34:35] op_sel_hi:[0,1,0]
	v_rcp_f32_e32 v37, v37
	v_rcp_f32_e32 v38, v38
	v_rcp_f32_e32 v39, v39
	v_pk_mul_f32 v[28:29], v[16:17], v[32:33] op_sel_hi:[1,0]
	v_pk_mul_f32 v[26:27], v[26:27], v[30:31]
	v_exp_f32_e32 v28, v28
	v_exp_f32_e32 v29, v29
	v_pk_mul_f32 v[30:31], v[18:19], v[32:33] op_sel_hi:[1,0]
	v_add_co_u32_e32 v44, vcc, s80, v132
	v_exp_f32_e32 v30, v30
	v_exp_f32_e32 v31, v31
	v_addc_co_u32_e32 v45, vcc, 0, v133, vcc
	v_pk_mul_f32 v[24:25], v[24:25], v[36:37]
	v_pk_mul_f32 v[26:27], v[26:27], v[38:39]
	global_store_dwordx4 v[44:45], v[40:43], off
	s_and_b64 vcc, s[6:7], s[12:13]
	s_cbranch_vccz .Lepibar2_p1
	s_barrier
.Lepibar2_p1:
	v_cvt_pk_bf16_f32 v24, v24, v25
	v_cvt_pk_bf16_f32 v25, v26, v27
	v_pk_fma_f32 v[26:27], v[34:35], v[28:29], v[34:35] op_sel_hi:[0,1,0]
	v_rcp_f32_e32 v26, v26
	v_rcp_f32_e32 v27, v27
	v_pk_fma_f32 v[28:29], v[34:35], v[30:31], v[34:35] op_sel_hi:[0,1,0]
	v_rcp_f32_e32 v28, v28
	v_rcp_f32_e32 v29, v29
	v_pk_mul_f32 v[16:17], v[16:17], v[20:21]
	v_pk_mul_f32 v[18:19], v[18:19], v[22:23]
	v_pk_mul_f32 v[16:17], v[16:17], v[26:27]
	v_pk_mul_f32 v[18:19], v[18:19], v[28:29]
	v_cvt_pk_bf16_f32 v26, v16, v17
	v_mul_f32_e32 v16, 0xbfb8aa3b, v135
	v_mul_f32_e32 v17, v135, v135
	v_pk_mul_f32 v[20:21], v[8:9], v[16:17] op_sel_hi:[1,0]
	v_pk_mul_f32 v[22:23], v[10:11], v[16:17] op_sel_hi:[1,0]
	v_cvt_pk_bf16_f32 v27, v18, v19
	v_rcp_f32_e32 v18, v17
	v_exp_f32_e32 v20, v20
	v_exp_f32_e32 v21, v21
	v_exp_f32_e32 v22, v22
	v_exp_f32_e32 v23, v23
	v_pk_mul_f32 v[8:9], v[8:9], v[12:13]
	v_pk_fma_f32 v[20:21], v[18:19], v[20:21], v[18:19] op_sel_hi:[0,1,0]
	v_rcp_f32_e32 v20, v20
	v_pk_fma_f32 v[22:23], v[18:19], v[22:23], v[18:19] op_sel_hi:[0,1,0]
	v_rcp_f32_e32 v21, v21
	v_rcp_f32_e32 v22, v22
	v_rcp_f32_e32 v23, v23
	v_pk_mul_f32 v[12:13], v[0:1], v[16:17] op_sel_hi:[1,0]
	v_add_co_u32_e32 v28, vcc, s81, v132
	v_exp_f32_e32 v12, v12
	v_exp_f32_e32 v13, v13
	v_pk_mul_f32 v[10:11], v[10:11], v[14:15]
	v_addc_co_u32_e32 v29, vcc, 0, v133, vcc
	v_pk_mul_f32 v[8:9], v[8:9], v[20:21]
	v_pk_mul_f32 v[10:11], v[10:11], v[22:23]
	v_pk_mul_f32 v[14:15], v[2:3], v[16:17] op_sel_hi:[1,0]
	global_store_dwordx4 v[28:29], v[24:27], off
	v_exp_f32_e32 v14, v14
	v_exp_f32_e32 v15, v15
	v_cvt_pk_bf16_f32 v8, v8, v9
	v_cvt_pk_bf16_f32 v9, v10, v11
	v_pk_fma_f32 v[10:11], v[18:19], v[12:13], v[18:19] op_sel_hi:[0,1,0]
	v_rcp_f32_e32 v10, v10
	v_rcp_f32_e32 v11, v11
	v_pk_fma_f32 v[12:13], v[18:19], v[14:15], v[18:19] op_sel_hi:[0,1,0]
	v_pk_mul_f32 v[0:1], v[0:1], v[4:5]
	v_rcp_f32_e32 v12, v12
	v_rcp_f32_e32 v13, v13
	v_pk_mul_f32 v[0:1], v[0:1], v[10:11]
	v_pk_mul_f32 v[2:3], v[2:3], v[6:7]
	v_cvt_pk_bf16_f32 v10, v0, v1
	v_add_co_u32_e32 v0, vcc, 0xf2000, v132
	v_pk_mul_f32 v[2:3], v[2:3], v[12:13]
	s_nop 0
	v_addc_co_u32_e32 v1, vcc, 0, v133, vcc
	s_andn2_b64 vcc, exec, s[6:7]
	s_mov_b64 s[6:7], -1
	v_cvt_pk_bf16_f32 v11, v2, v3
	global_store_dwordx4 v[0:1], v[8:11], off
	s_cbranch_vccnz .LBB0_520
	s_andn2_b64 vcc, exec, s[12:13]
	s_cbranch_vccnz .LBB0_519
	s_nop 0
	s_branch .LBB0_519

.Lepibar_p6:
	v_cvt_pk_bf16_f32 v88, v88, v89
	v_cvt_pk_bf16_f32 v89, v90, v91
	v_pk_fma_f32 v[90:91], v[98:99], v[92:93], v[98:99] op_sel_hi:[0,1,0]
	v_rcp_f32_e32 v90, v90
	v_rcp_f32_e32 v91, v91
	v_pk_fma_f32 v[92:93], v[98:99], v[94:95], v[98:99] op_sel_hi:[0,1,0]
	v_rcp_f32_e32 v92, v92
	v_rcp_f32_e32 v93, v93
	v_pk_mul_f32 v[80:81], v[80:81], v[84:85]
	v_pk_mul_f32 v[82:83], v[82:83], v[86:87]
	v_pk_mul_f32 v[80:81], v[80:81], v[90:91]
	v_pk_mul_f32 v[82:83], v[82:83], v[92:93]
	v_cvt_pk_bf16_f32 v90, v80, v81
	v_mul_f32_e32 v80, 0xbfb8aa3b, v139
	v_mul_f32_e32 v81, v139, v139
	v_pk_mul_f32 v[84:85], v[72:73], v[80:81] op_sel_hi:[1,0]
	v_pk_mul_f32 v[86:87], v[74:75], v[80:81] op_sel_hi:[1,0]
	v_cvt_pk_bf16_f32 v91, v82, v83
	v_rcp_f32_e32 v82, v81
	v_exp_f32_e32 v84, v84
	v_exp_f32_e32 v85, v85
	v_exp_f32_e32 v86, v86
	v_exp_f32_e32 v87, v87
	v_pk_mul_f32 v[72:73], v[72:73], v[76:77]
	v_pk_fma_f32 v[84:85], v[82:83], v[84:85], v[82:83] op_sel_hi:[0,1,0]
	v_rcp_f32_e32 v84, v84
	v_pk_fma_f32 v[86:87], v[82:83], v[86:87], v[82:83] op_sel_hi:[0,1,0]
	v_rcp_f32_e32 v85, v85
	v_rcp_f32_e32 v86, v86
	v_rcp_f32_e32 v87, v87
	v_pk_mul_f32 v[76:77], v[56:57], v[80:81] op_sel_hi:[1,0]
	v_pk_mul_f32 v[74:75], v[74:75], v[78:79]
	v_exp_f32_e32 v76, v76
	v_exp_f32_e32 v77, v77
	v_pk_mul_f32 v[78:79], v[58:59], v[80:81] op_sel_hi:[1,0]
	v_add_co_u32_e32 v92, vcc, s69, v132
	v_exp_f32_e32 v78, v78
	v_exp_f32_e32 v79, v79
	v_addc_co_u32_e32 v93, vcc, 0, v133, vcc
	v_pk_mul_f32 v[72:73], v[72:73], v[84:85]
	v_pk_mul_f32 v[74:75], v[74:75], v[86:87]
	global_store_dwordx4 v[92:93], v[88:91], off
	v_cvt_pk_bf16_f32 v72, v72, v73
	v_cvt_pk_bf16_f32 v73, v74, v75
	v_pk_fma_f32 v[74:75], v[82:83], v[76:77], v[82:83] op_sel_hi:[0,1,0]
	v_rcp_f32_e32 v74, v74
	v_rcp_f32_e32 v75, v75
	v_pk_fma_f32 v[76:77], v[82:83], v[78:79], v[82:83] op_sel_hi:[0,1,0]
	v_rcp_f32_e32 v76, v76
	v_rcp_f32_e32 v77, v77
	v_pk_mul_f32 v[56:57], v[56:57], v[64:65]
	v_pk_mul_f32 v[58:59], v[58:59], v[66:67]
	v_pk_mul_f32 v[56:57], v[56:57], v[74:75]
	v_pk_mul_f32 v[58:59], v[58:59], v[76:77]
	v_cvt_pk_bf16_f32 v74, v56, v57
	s_waitcnt lgkmcnt(1)
	v_mul_f32_e32 v56, 0xbfb8aa3b, v136
	v_mul_f32_e32 v57, v136, v136
	v_pk_mul_f32 v[64:65], v[60:61], v[56:57] op_sel_hi:[1,0]
	v_cvt_pk_bf16_f32 v75, v58, v59
	v_rcp_f32_e32 v58, v57
	v_exp_f32_e32 v64, v64
	v_exp_f32_e32 v65, v65
	v_pk_mul_f32 v[66:67], v[62:63], v[56:57] op_sel_hi:[1,0]
	v_pk_mul_f32 v[60:61], v[60:61], v[68:69]
	v_exp_f32_e32 v66, v66
	v_exp_f32_e32 v67, v67
	v_pk_fma_f32 v[64:65], v[58:59], v[64:65], v[58:59] op_sel_hi:[0,1,0]
	v_rcp_f32_e32 v64, v64
	v_rcp_f32_e32 v65, v65
	v_pk_fma_f32 v[66:67], v[58:59], v[66:67], v[58:59] op_sel_hi:[0,1,0]
	v_rcp_f32_e32 v66, v66
	v_rcp_f32_e32 v67, v67
	v_pk_mul_f32 v[60:61], v[60:61], v[64:65]
	v_pk_mul_f32 v[64:65], v[48:49], v[56:57] op_sel_hi:[1,0]
	v_pk_mul_f32 v[62:63], v[62:63], v[70:71]
	v_pk_mul_f32 v[56:57], v[50:51], v[56:57] op_sel_hi:[1,0]
	v_exp_f32_e32 v64, v64
	v_exp_f32_e32 v65, v65
	v_pk_mul_f32 v[62:63], v[62:63], v[66:67]
	v_exp_f32_e32 v66, v56
	v_exp_f32_e32 v67, v57
	v_add_co_u32_e32 v76, vcc, s70, v132
	v_pk_mul_f32 v[48:49], v[48:49], v[52:53]
	s_nop 0
	v_addc_co_u32_e32 v77, vcc, 0, v133, vcc
	global_store_dwordx4 v[76:77], v[72:75], off
	v_cvt_pk_bf16_f32 v56, v60, v61
	v_pk_fma_f32 v[60:61], v[58:59], v[64:65], v[58:59] op_sel_hi:[0,1,0]
	v_pk_fma_f32 v[58:59], v[58:59], v[66:67], v[58:59] op_sel_hi:[0,1,0]
	v_rcp_f32_e32 v60, v60
	v_rcp_f32_e32 v61, v61
	v_rcp_f32_e32 v58, v58
	v_rcp_f32_e32 v59, v59
	v_pk_mul_f32 v[50:51], v[50:51], v[54:55]
	v_pk_mul_f32 v[48:49], v[48:49], v[60:61]
	v_cvt_pk_bf16_f32 v57, v62, v63
	v_pk_mul_f32 v[50:51], v[50:51], v[58:59]
	v_cvt_pk_bf16_f32 v58, v48, v49
	v_mul_f32_e32 v48, 0xbfb8aa3b, v137
	v_mul_f32_e32 v49, v137, v137
	v_pk_mul_f32 v[52:53], v[40:41], v[48:49] op_sel_hi:[1,0]
	v_pk_mul_f32 v[54:55], v[42:43], v[48:49] op_sel_hi:[1,0]
	v_cvt_pk_bf16_f32 v59, v50, v51
	v_rcp_f32_e32 v50, v49
	v_exp_f32_e32 v52, v52
	v_exp_f32_e32 v53, v53
	v_exp_f32_e32 v54, v54
	v_exp_f32_e32 v55, v55
	v_pk_mul_f32 v[40:41], v[40:41], v[44:45]
	v_pk_fma_f32 v[52:53], v[50:51], v[52:53], v[50:51] op_sel_hi:[0,1,0]
	v_rcp_f32_e32 v52, v52
	v_pk_fma_f32 v[54:55], v[50:51], v[54:55], v[50:51] op_sel_hi:[0,1,0]
	v_rcp_f32_e32 v53, v53
	v_rcp_f32_e32 v54, v54
	v_rcp_f32_e32 v55, v55
	v_pk_mul_f32 v[44:45], v[32:33], v[48:49] op_sel_hi:[1,0]
	v_pk_mul_f32 v[42:43], v[42:43], v[46:47]
	v_exp_f32_e32 v44, v44
	v_exp_f32_e32 v45, v45
	v_pk_mul_f32 v[46:47], v[34:35], v[48:49] op_sel_hi:[1,0]
	v_add_co_u32_e32 v60, vcc, s71, v132
	v_exp_f32_e32 v46, v46
	v_exp_f32_e32 v47, v47
	v_addc_co_u32_e32 v61, vcc, 0, v133, vcc
	v_pk_mul_f32 v[40:41], v[40:41], v[52:53]
	v_pk_mul_f32 v[42:43], v[42:43], v[54:55]
	global_store_dwordx4 v[60:61], v[56:59], off
	v_cvt_pk_bf16_f32 v40, v40, v41
	v_cvt_pk_bf16_f32 v41, v42, v43
	v_pk_fma_f32 v[42:43], v[50:51], v[44:45], v[50:51] op_sel_hi:[0,1,0]
	v_rcp_f32_e32 v42, v42
	v_rcp_f32_e32 v43, v43
	v_pk_fma_f32 v[44:45], v[50:51], v[46:47], v[50:51] op_sel_hi:[0,1,0]
	v_rcp_f32_e32 v44, v44
	v_rcp_f32_e32 v45, v45
	v_pk_mul_f32 v[32:33], v[32:33], v[36:37]
	v_pk_mul_f32 v[34:35], v[34:35], v[38:39]
	v_pk_mul_f32 v[32:33], v[32:33], v[42:43]
	v_pk_mul_f32 v[34:35], v[34:35], v[44:45]
	v_cvt_pk_bf16_f32 v42, v32, v33
	s_waitcnt lgkmcnt(0)
	v_mul_f32_e32 v32, 0xbfb8aa3b, v134
	v_mul_f32_e32 v33, v134, v134
	v_pk_mul_f32 v[36:37], v[24:25], v[32:33] op_sel_hi:[1,0]
	v_pk_mul_f32 v[38:39], v[26:27], v[32:33] op_sel_hi:[1,0]
	v_cvt_pk_bf16_f32 v43, v34, v35
	v_rcp_f32_e32 v34, v33
	v_exp_f32_e32 v36, v36
	v_exp_f32_e32 v37, v37
	v_exp_f32_e32 v38, v38
	v_exp_f32_e32 v39, v39
	v_pk_mul_f32 v[24:25], v[24:25], v[28:29]
	v_pk_fma_f32 v[36:37], v[34:35], v[36:37], v[34:35] op_sel_hi:[0,1,0]
	v_rcp_f32_e32 v36, v36
	v_pk_fma_f32 v[38:39], v[34:35], v[38:39], v[34:35] op_sel_hi:[0,1,0]
	v_rcp_f32_e32 v37, v37
	v_rcp_f32_e32 v38, v38
	v_rcp_f32_e32 v39, v39
	v_pk_mul_f32 v[28:29], v[16:17], v[32:33] op_sel_hi:[1,0]
	v_pk_mul_f32 v[26:27], v[26:27], v[30:31]
	v_exp_f32_e32 v28, v28
	v_exp_f32_e32 v29, v29
	v_pk_mul_f32 v[30:31], v[18:19], v[32:33] op_sel_hi:[1,0]
	v_add_co_u32_e32 v44, vcc, s72, v132
	v_exp_f32_e32 v30, v30
	v_exp_f32_e32 v31, v31
	v_addc_co_u32_e32 v45, vcc, 0, v133, vcc
	v_pk_mul_f32 v[24:25], v[24:25], v[36:37]
	v_pk_mul_f32 v[26:27], v[26:27], v[38:39]
	global_store_dwordx4 v[44:45], v[40:43], off
	s_and_b64 vcc, s[0:1], s[6:7]
	s_cbranch_vccz .Lepibar2_p6
	s_barrier
.Lepibar2_p6:
	v_cvt_pk_bf16_f32 v24, v24, v25
	v_cvt_pk_bf16_f32 v25, v26, v27
	v_pk_fma_f32 v[26:27], v[34:35], v[28:29], v[34:35] op_sel_hi:[0,1,0]
	v_rcp_f32_e32 v26, v26
	v_rcp_f32_e32 v27, v27
	v_pk_fma_f32 v[28:29], v[34:35], v[30:31], v[34:35] op_sel_hi:[0,1,0]
	v_rcp_f32_e32 v28, v28
	v_rcp_f32_e32 v29, v29
	v_pk_mul_f32 v[16:17], v[16:17], v[20:21]
	v_pk_mul_f32 v[18:19], v[18:19], v[22:23]
	v_pk_mul_f32 v[16:17], v[16:17], v[26:27]
	v_pk_mul_f32 v[18:19], v[18:19], v[28:29]
	v_cvt_pk_bf16_f32 v26, v16, v17
	v_mul_f32_e32 v16, 0xbfb8aa3b, v135
	v_mul_f32_e32 v17, v135, v135
	v_pk_mul_f32 v[20:21], v[8:9], v[16:17] op_sel_hi:[1,0]
	v_pk_mul_f32 v[22:23], v[10:11], v[16:17] op_sel_hi:[1,0]
	v_cvt_pk_bf16_f32 v27, v18, v19
	v_rcp_f32_e32 v18, v17
	v_exp_f32_e32 v20, v20
	v_exp_f32_e32 v21, v21
	v_exp_f32_e32 v22, v22
	v_exp_f32_e32 v23, v23
	v_pk_mul_f32 v[8:9], v[8:9], v[12:13]
	v_pk_fma_f32 v[20:21], v[18:19], v[20:21], v[18:19] op_sel_hi:[0,1,0]
	v_rcp_f32_e32 v20, v20
	v_pk_fma_f32 v[22:23], v[18:19], v[22:23], v[18:19] op_sel_hi:[0,1,0]
	v_rcp_f32_e32 v21, v21
	v_rcp_f32_e32 v22, v22
	v_rcp_f32_e32 v23, v23
	v_pk_mul_f32 v[12:13], v[0:1], v[16:17] op_sel_hi:[1,0]
	v_add_co_u32_e32 v28, vcc, s73, v132
	v_exp_f32_e32 v12, v12
	v_exp_f32_e32 v13, v13
	v_pk_mul_f32 v[10:11], v[10:11], v[14:15]
	v_addc_co_u32_e32 v29, vcc, 0, v133, vcc
	v_pk_mul_f32 v[8:9], v[8:9], v[20:21]
	v_pk_mul_f32 v[10:11], v[10:11], v[22:23]
	v_pk_mul_f32 v[14:15], v[2:3], v[16:17] op_sel_hi:[1,0]
	global_store_dwordx4 v[28:29], v[24:27], off
	v_exp_f32_e32 v14, v14
	v_exp_f32_e32 v15, v15
	v_cvt_pk_bf16_f32 v8, v8, v9
	v_cvt_pk_bf16_f32 v9, v10, v11
	v_pk_fma_f32 v[10:11], v[18:19], v[12:13], v[18:19] op_sel_hi:[0,1,0]
	v_rcp_f32_e32 v10, v10
	v_rcp_f32_e32 v11, v11
	v_pk_fma_f32 v[12:13], v[18:19], v[14:15], v[18:19] op_sel_hi:[0,1,0]
	v_pk_mul_f32 v[0:1], v[0:1], v[4:5]
	v_rcp_f32_e32 v12, v12
	v_rcp_f32_e32 v13, v13
	v_pk_mul_f32 v[0:1], v[0:1], v[10:11]
	v_pk_mul_f32 v[2:3], v[2:3], v[6:7]
	v_cvt_pk_bf16_f32 v10, v0, v1
	v_add_co_u32_e32 v0, vcc, 0xf2000, v132
	v_pk_mul_f32 v[2:3], v[2:3], v[12:13]
	s_nop 0
	v_addc_co_u32_e32 v1, vcc, 0, v133, vcc
	s_andn2_b64 vcc, exec, s[0:1]
	s_mov_b64 s[0:1], -1
	v_cvt_pk_bf16_f32 v11, v2, v3
	global_store_dwordx4 v[0:1], v[8:11], off
	s_cbranch_vccnz .LBB0_1250
	s_andn2_b64 vcc, exec, s[6:7]
	s_cbranch_vccnz .LBB0_1249
	s_nop 0
	s_branch .LBB0_1249
